# k3 phase: static item loop replaced by dynamic atomic work queue (load balance)
# speedup vs baseline: 1.2262x; 1.2262x over previous
; #define ITEMS_STATIC(item, total) for (int item = (__syncthreads(), (int)blockIdx.x); item < (total); item = (__syncthreads(), item + (int)gridDim.x))
; DI int next_item(unsigned* ctr, int* s_item) {
;   __syncthreads();
;   if (threadIdx.x == 0) *s_item = (int)atomicAdd(ctr, 1u);
;   __syncthreads();
;   return *s_item;
; }
; __global__ void __launch_bounds__(256, 2) mega(P p) {
;     ...
;         constexpr int NC = 8 * NCH, NGT = 66 * 16;
;         ITEMS_STATIC(item, NC + NGT + T / 4) {
.LBB0_175:
	s_or_b64 exec, exec, s[0:1]
.LBB0_176:
	s_barrier
.Lk3_fetch:
	s_and_saveexec_b64 s[0:1], s[96:97]
	s_cbranch_execz .Lk3_fetched
	v_readlane_b32 s98, v255, 4
	v_mov_b32_e32 v1, 1
	s_lshl_b32 s98, s98, 2
	s_add_u32 s98, s94, s98
	s_addc_u32 s99, s95, 0
	s_nop 0
	global_atomic_add v1, v97, v1, s[98:99] sc0
	s_waitcnt vmcnt(0)
	ds_write_b32 v205, v1
.Lk3_fetched:
	s_or_b64 exec, exec, s[0:1]
	s_waitcnt lgkmcnt(0)
	s_barrier
	ds_read_b32 v0, v205
	s_waitcnt lgkmcnt(0)
	v_readfirstlane_b32 s80, v0
	s_cmpk_gt_i32 s80, 0x107f
	s_cbranch_scc1 .LBB0_288
